# attention: non-lag waves stage their part of K/V tile kt+2 at the end of their MFMA half (was tile kt+1 at the head of the softmax half)
# speedup vs baseline: 1.0103x; 1.0084x over previous
.LBB0_227:
	s_lshl_b32 s4, s59, 11
	s_and_b32 s5, s4, 0x1000000
	s_lshl_b32 s4, s36, 4
	s_and_b32 s28, s4, 0x700
	v_lshl_or_b32 v96, v148, 1, s28
	v_or_b32_e32 v96, s5, v96
	v_mov_b32_e32 v97, v209
	s_lshl_b32 s21, s21, 9
	s_mov_b32 s65, 2
	s_add_i32 s66, s8, 2
	s_mov_b32 s4, 1
	v_lshl_add_u64 v[174:175], v[170:171], 0, v[96:97]
	v_subrev_u32_e32 v204, s21, v194
	s_add_i32 s33, s61, s8
	s_mov_b32 s87, 0
	s_movk_i32 s68, 0xff00
	s_waitcnt lgkmcnt(0)
	s_barrier
	s_and_b64 vcc, exec, s[16:17]
	s_cbranch_vccnz .LBB0_228
	s_mov_b32 s5, 0
	s_mov_b32 s28, 0xa000
	s_cmp_ge_u32 s65, s66
	s_cbranch_scc1 .Latt_p_qk
	v_add_u32_e32 v176, s5, v157
	s_waitcnt vmcnt(3)
	ds_write_b128 v176, v[128:131]
	v_add_u32_e32 v176, s28, v159
	s_waitcnt vmcnt(2)
	ds_write_b128 v176, v[132:135] offset:34816
	v_add_u32_e32 v176, s5, v161
	s_waitcnt vmcnt(1)
	ds_write_b128 v176, v[136:139]
	v_add_u32_e32 v176, s28, v163
	s_cmp_lt_u32 s8, 2
	s_waitcnt vmcnt(0)
	ds_write_b128 v176, v[140:143] offset:34816
	s_cbranch_scc1 .Latt_p_shift
	v_add_co_u32_e32 v176, vcc, 0xf5ff0000, v174
	s_nop 1
	v_addc_co_u32_e32 v177, vcc, -1, v175, vcc
	v_add_co_u32_e32 v178, vcc, 0xffff0000, v174
	s_nop 1
	v_addc_co_u32_e32 v179, vcc, -1, v175, vcc
	global_load_dwordx4 v[128:131], v[176:177], off
	global_load_dwordx4 v[132:135], v[178:179], off
	v_add_co_u32_e32 v176, vcc, 0xf6000000, v174
	s_nop 1
	v_addc_co_u32_e32 v177, vcc, -1, v175, vcc
	global_load_dwordx4 v[136:139], v[176:177], off
	global_load_dwordx4 v[140:143], v[174:175], off
.Latt_p_shift:
	v_lshl_add_u64 v[174:175], v[174:175], 0, s[78:79]
.Latt_p_qk:
	s_cmp_lt_i32 s9, 1
	s_cbranch_scc1 .LBB0_228
	s_movk_i32 s5, 0x4400
	v_add_u32_e32 v205, s5, v192
	ds_read_b128 v[96:99], v205 offset:8704
	ds_read_b128 v[100:103], v205 offset:8736
	ds_read_b128 v[104:107], v205 offset:8768
	ds_read_b128 v[108:111], v205 offset:8800
	ds_read_b128 v[176:179], v205
	ds_read_b128 v[180:183], v205 offset:32
	ds_read_b128 v[184:187], v205 offset:64
	ds_read_b128 v[188:191], v205 offset:96
	s_waitcnt lgkmcnt(7)
	v_mfma_f32_32x32x16_bf16 v[80:95], v[96:99], v[112:115], v[64:79]
	s_waitcnt lgkmcnt(6)
	v_mfma_f32_32x32x16_bf16 v[80:95], v[100:103], v[116:119], v[80:95]
	s_waitcnt lgkmcnt(5)
	v_mfma_f32_32x32x16_bf16 v[80:95], v[104:107], v[120:123], v[80:95]
	s_waitcnt lgkmcnt(4)
	v_mfma_f32_32x32x16_bf16 v[80:95], v[108:111], v[124:127], v[80:95]
	s_waitcnt lgkmcnt(3)
	v_mfma_f32_32x32x16_bf16 v[96:111], v[176:179], v[112:115], v[64:79]
	s_waitcnt lgkmcnt(2)
	v_mfma_f32_32x32x16_bf16 v[96:111], v[180:183], v[116:119], v[96:111]
	s_waitcnt lgkmcnt(1)
	v_mfma_f32_32x32x16_bf16 v[96:111], v[184:187], v[120:123], v[96:111]
	s_waitcnt lgkmcnt(0)
	v_mfma_f32_32x32x16_bf16 v[96:111], v[188:191], v[124:127], v[96:111]
	s_cmp_gt_i32 s33, 2
	s_cbranch_scc1 .LBB0_228
	s_waitcnt lgkmcnt(0)
	v_add_u32_e32 v205, s68, v204
	v_add_u32_e32 v176, 0x17d00, v205
	v_add_u32_e32 v178, 0x17d80, v205
	ds_read2_b32 v[176:177], v176 offset1:1
	ds_read2_b32 v[178:179], v178 offset1:1
	v_add_u32_e32 v180, 0x17d08, v205
	v_add_u32_e32 v182, 0x17d88, v205
	v_add_u32_e32 v184, 0x17d20, v205
	v_add_u32_e32 v186, 0x17da0, v205
	v_add_u32_e32 v188, 0x17d28, v205
	v_add_u32_e32 v190, 0x17da8, v205
	v_add_u32_e32 v206, 0x17d40, v205
	v_add_u32_e32 v210, 0x17dc0, v205
	v_add_u32_e32 v212, 0x17d48, v205
	v_add_u32_e32 v221, 0x17dc8, v205
	ds_read2_b32 v[180:181], v180 offset1:1
	ds_read2_b32 v[182:183], v182 offset1:1
	ds_read2_b32 v[184:185], v184 offset1:1
	ds_read2_b32 v[186:187], v186 offset1:1
	ds_read2_b32 v[188:189], v188 offset1:1
	ds_read2_b32 v[190:191], v190 offset1:1
	ds_read2_b32 v[206:207], v206 offset1:1
	ds_read2_b32 v[210:211], v210 offset1:1
	ds_read2_b32 v[212:213], v212 offset1:1
	ds_read2_b32 v[224:225], v221 offset1:1
	v_add_u32_e32 v221, 0x17d60, v205
	v_add_u32_e32 v223, 0x17de0, v205
	ds_read2_b32 v[226:227], v221 offset1:1
	ds_read2_b32 v[228:229], v223 offset1:1
	v_add_u32_e32 v221, 0x17d68, v205
	v_add_u32_e32 v205, 0x17de8, v205
	ds_read2_b32 v[230:231], v221 offset1:1
	s_waitcnt lgkmcnt(14)
	v_pk_add_f32 v[96:97], v[96:97], v[176:177]
	ds_read2_b32 v[176:177], v205 offset1:1
	s_waitcnt lgkmcnt(3)
	v_pk_add_f32 v[108:109], v[108:109], v[226:227]
	v_pk_add_f32 v[106:107], v[106:107], v[212:213]
	s_waitcnt lgkmcnt(1)
	v_pk_add_f32 v[110:111], v[110:111], v[230:231]
	v_pk_add_f32 v[104:105], v[104:105], v[206:207]
	v_pk_add_f32 v[102:103], v[102:103], v[188:189]
	v_pk_add_f32 v[100:101], v[100:101], v[184:185]
	v_pk_add_f32 v[98:99], v[98:99], v[180:181]
	s_waitcnt lgkmcnt(0)
	v_pk_add_f32 v[94:95], v[94:95], v[176:177]
	v_pk_add_f32 v[92:93], v[92:93], v[228:229]
	v_pk_add_f32 v[90:91], v[90:91], v[224:225]
	v_pk_add_f32 v[88:89], v[88:89], v[210:211]
	v_pk_add_f32 v[86:87], v[86:87], v[190:191]
	v_pk_add_f32 v[84:85], v[84:85], v[186:187]
	v_pk_add_f32 v[82:83], v[82:83], v[182:183]
	v_pk_add_f32 v[80:81], v[80:81], v[178:179]
	s_nop 0
.LBB0_228:
	s_add_i32 s86, s65, -1
	s_bitcmp0_b32 s86, 0
	s_mov_b32 s69, s4
	s_cselect_b32 s28, 0x4400, 0
	s_cselect_b32 s5, 0, 0x4400
	s_mul_i32 s29, s69, 0x5000
	s_addk_i32 s29, 0x5000
	s_cmp_lg_u32 s69, 2
	s_cselect_b32 s29, s29, 0
	s_and_b64 vcc, exec, s[16:17]
	s_cbranch_vccnz .Latt_a
	s_cmp_gt_i32 s86, s9
	s_cbranch_scc1 .Latt_b_bar
	v_max_f32_e32 v176, v80, v80
	v_max_f32_e32 v177, v96, v96
	v_max_f32_e32 v176, v177, v176
	v_max3_f32 v177, v81, v98, v82
	v_max3_f32 v176, v176, v97, v99
	v_max3_f32 v177, v177, v100, v84
	v_max3_f32 v176, v176, v83, v101
	v_max3_f32 v177, v177, v102, v86
	v_max3_f32 v176, v176, v85, v103
	v_max3_f32 v177, v177, v104, v88
	v_max3_f32 v176, v176, v87, v105
	v_max3_f32 v177, v177, v106, v90
	v_max3_f32 v176, v176, v89, v107
	v_max3_f32 v177, v177, v108, v92
	v_max3_f32 v176, v176, v91, v109
	v_max3_f32 v177, v177, v110, v94
	v_max3_f32 v176, v176, v93, v111
	v_max3_f32 v176, v176, v95, v177
	v_mov_b32_e32 v177, v176
	s_nop 1
	v_permlane32_swap_b32_e32 v176, v177
	v_max_f32_e32 v177, v177, v177
	v_max_f32_e32 v176, v176, v176
	v_max_f32_e32 v176, v176, v177
	s_mov_b32 s4, 0x41000000
	v_cmp_lt_f32_e32 vcc, s4, v176
	s_cbranch_vccz .Latt_b_exp
	v_max_f32_e32 v64, v176, v176
	v_max_f32_e32 v66, 0, v64
	v_exp_f32_e64 v176, -v66
	v_add_f32_e32 v173, v173, v66
	v_xor_b32_e32 v64, 0x80000000, v173
	v_pk_add_f32 v[96:97], v[96:97], v[66:67] op_sel_hi:[1,0] neg_lo:[0,1] neg_hi:[0,1]
	v_pk_add_f32 v[80:81], v[80:81], v[66:67] op_sel_hi:[1,0] neg_lo:[0,1] neg_hi:[0,1]
	v_pk_add_f32 v[98:99], v[98:99], v[66:67] op_sel_hi:[1,0] neg_lo:[0,1] neg_hi:[0,1]
	v_pk_add_f32 v[82:83], v[82:83], v[66:67] op_sel_hi:[1,0] neg_lo:[0,1] neg_hi:[0,1]
	v_pk_add_f32 v[100:101], v[100:101], v[66:67] op_sel_hi:[1,0] neg_lo:[0,1] neg_hi:[0,1]
	v_pk_add_f32 v[84:85], v[84:85], v[66:67] op_sel_hi:[1,0] neg_lo:[0,1] neg_hi:[0,1]
	v_pk_add_f32 v[102:103], v[102:103], v[66:67] op_sel_hi:[1,0] neg_lo:[0,1] neg_hi:[0,1]
	v_pk_add_f32 v[86:87], v[86:87], v[66:67] op_sel_hi:[1,0] neg_lo:[0,1] neg_hi:[0,1]
	v_pk_add_f32 v[104:105], v[104:105], v[66:67] op_sel_hi:[1,0] neg_lo:[0,1] neg_hi:[0,1]
	v_pk_add_f32 v[88:89], v[88:89], v[66:67] op_sel_hi:[1,0] neg_lo:[0,1] neg_hi:[0,1]
	v_pk_add_f32 v[106:107], v[106:107], v[66:67] op_sel_hi:[1,0] neg_lo:[0,1] neg_hi:[0,1]
	v_pk_add_f32 v[90:91], v[90:91], v[66:67] op_sel_hi:[1,0] neg_lo:[0,1] neg_hi:[0,1]
	v_pk_add_f32 v[108:109], v[108:109], v[66:67] op_sel_hi:[1,0] neg_lo:[0,1] neg_hi:[0,1]
	v_pk_add_f32 v[92:93], v[92:93], v[66:67] op_sel_hi:[1,0] neg_lo:[0,1] neg_hi:[0,1]
	v_pk_add_f32 v[110:111], v[110:111], v[66:67] op_sel_hi:[1,0] neg_lo:[0,1] neg_hi:[0,1]
	v_pk_add_f32 v[94:95], v[94:95], v[66:67] op_sel_hi:[1,0] neg_lo:[0,1] neg_hi:[0,1]
	v_mov_b32_e32 v65, v64
	v_mov_b32_e32 v66, v64
	v_mov_b32_e32 v67, v64
	v_mov_b32_e32 v68, v64
	v_mov_b32_e32 v69, v64
	v_mov_b32_e32 v70, v64
	v_mov_b32_e32 v71, v64
	v_mov_b32_e32 v72, v64
	v_mov_b32_e32 v73, v64
	v_mov_b32_e32 v74, v64
	v_mov_b32_e32 v75, v64
	v_mov_b32_e32 v76, v64
	v_mov_b32_e32 v77, v64
	v_mov_b32_e32 v78, v64
	v_mov_b32_e32 v79, v64
	v_pk_mul_f32 v[46:47], v[46:47], v[176:177] op_sel_hi:[1,0]
	v_pk_mul_f32 v[44:45], v[44:45], v[176:177] op_sel_hi:[1,0]
	v_pk_mul_f32 v[42:43], v[42:43], v[176:177] op_sel_hi:[1,0]
	v_pk_mul_f32 v[40:41], v[40:41], v[176:177] op_sel_hi:[1,0]
	v_pk_mul_f32 v[38:39], v[38:39], v[176:177] op_sel_hi:[1,0]
	v_pk_mul_f32 v[36:37], v[36:37], v[176:177] op_sel_hi:[1,0]
	v_pk_mul_f32 v[34:35], v[34:35], v[176:177] op_sel_hi:[1,0]
	v_pk_mul_f32 v[32:33], v[32:33], v[176:177] op_sel_hi:[1,0]
	v_pk_mul_f32 v[30:31], v[30:31], v[176:177] op_sel_hi:[1,0]
	v_pk_mul_f32 v[28:29], v[28:29], v[176:177] op_sel_hi:[1,0]
	v_pk_mul_f32 v[26:27], v[26:27], v[176:177] op_sel_hi:[1,0]
	v_pk_mul_f32 v[24:25], v[24:25], v[176:177] op_sel_hi:[1,0]
	v_pk_mul_f32 v[22:23], v[22:23], v[176:177] op_sel_hi:[1,0]
	v_pk_mul_f32 v[20:21], v[20:21], v[176:177] op_sel_hi:[1,0]
	v_pk_mul_f32 v[18:19], v[18:19], v[176:177] op_sel_hi:[1,0]
	v_pk_mul_f32 v[16:17], v[16:17], v[176:177] op_sel_hi:[1,0]
	v_pk_mul_f32 v[14:15], v[14:15], v[176:177] op_sel_hi:[1,0]
	v_pk_mul_f32 v[12:13], v[12:13], v[176:177] op_sel_hi:[1,0]
	v_pk_mul_f32 v[10:11], v[10:11], v[176:177] op_sel_hi:[1,0]
	v_pk_mul_f32 v[8:9], v[8:9], v[176:177] op_sel_hi:[1,0]
	v_pk_mul_f32 v[6:7], v[6:7], v[176:177] op_sel_hi:[1,0]
	v_pk_mul_f32 v[4:5], v[4:5], v[176:177] op_sel_hi:[1,0]
	v_pk_mul_f32 v[2:3], v[2:3], v[176:177] op_sel_hi:[1,0]
	v_pk_mul_f32 v[0:1], v[0:1], v[176:177] op_sel_hi:[1,0]
	v_pk_mul_f32 v[62:63], v[62:63], v[176:177] op_sel_hi:[1,0]
	v_pk_mul_f32 v[60:61], v[60:61], v[176:177] op_sel_hi:[1,0]
	v_pk_mul_f32 v[58:59], v[58:59], v[176:177] op_sel_hi:[1,0]
	v_pk_mul_f32 v[56:57], v[56:57], v[176:177] op_sel_hi:[1,0]
	v_pk_mul_f32 v[54:55], v[54:55], v[176:177] op_sel_hi:[1,0]
	v_pk_mul_f32 v[52:53], v[52:53], v[176:177] op_sel_hi:[1,0]
	v_pk_mul_f32 v[50:51], v[50:51], v[176:177] op_sel_hi:[1,0]
	v_pk_mul_f32 v[48:49], v[48:49], v[176:177] op_sel_hi:[1,0]
	v_mul_f32_e32 v172, v172, v176

.Latt_b_stg:
	s_mul_i32 s29, s87, 0x5000
	s_add_i32 s28, s65, 1
	s_cmp_ge_u32 s28, s66
	s_cbranch_scc1 .LBB0_241
	v_add_u32_e32 v176, s5, v157
	s_waitcnt vmcnt(3)
	ds_write_b128 v176, v[128:131]
	v_add_u32_e32 v176, s29, v159
	s_waitcnt vmcnt(2)
	ds_write_b128 v176, v[132:135] offset:34816
	v_add_u32_e32 v176, s5, v161
	s_waitcnt vmcnt(1)
	ds_write_b128 v176, v[136:139]
	v_add_u32_e32 v176, s29, v163
	s_add_i32 s28, s86, 1
	s_cmp_ge_u32 s28, s8
	s_waitcnt vmcnt(0)
	ds_write_b128 v176, v[140:143] offset:34816
	s_cbranch_scc1 .LBB0_241
	v_add_co_u32_e32 v176, vcc, 0xf5ff0000, v174
	s_nop 1
	v_addc_co_u32_e32 v177, vcc, -1, v175, vcc
	v_add_co_u32_e32 v178, vcc, 0xffff0000, v174
	s_nop 1
	v_addc_co_u32_e32 v179, vcc, -1, v175, vcc
	global_load_dwordx4 v[128:131], v[176:177], off
	global_load_dwordx4 v[132:135], v[178:179], off
	v_add_co_u32_e32 v176, vcc, 0xf6000000, v174
	s_nop 1
	v_addc_co_u32_e32 v177, vcc, -1, v175, vcc
	global_load_dwordx4 v[136:139], v[176:177], off
	global_load_dwordx4 v[140:143], v[174:175], off
	s_branch .LBB0_241
